# P1+P3+P9 K-loops: LDS-DMA addresses from SGPR bases, no VALU in load segments; SWA O stores dwordx4
# baseline (speedup 1.0000x reference)
; #define PG8_STAGE(bufoff, gbase, voff) do { _Pragma("unroll") for (int _i = 0; _i < 2; ++_i) \
;         __builtin_amdgcn_global_load_lds((const unsigned*)((const char*)(gbase) + (voff)[_i]), (PG8_LAS unsigned*)(lds + (bufoff) + ldsw + _i * 8192), 16, 0, 0); } while (0)
; #define PG8_LDA(dst, b, h) do { _Pragma("unroll") for (int m = 0; m < 4; ++m) _Pragma("unroll") for (int k = 0; k < 2; ++k) dst[m][k] = *(const PG8_LAS bf16x8*)(lds + PG8_SA(b, h) + aoff + m * 2048 + k * 1024); } while (0)
; #define PG8_LDB(dst, b, h) do { _Pragma("unroll") for (int n = 0; n < 2; ++n) _Pragma("unroll") for (int k = 0; k < 2; ++k) dst[n][k] = *(const PG8_LAS bf16x8*)(lds + PG8_SB(b, h) + boff + n * 2048 + k * 1024); } while (0)
; #define PG8_MMA(ai, bj, At, Bt) do { __builtin_amdgcn_s_setprio(1); _Pragma("unroll") for (int m = 0; m < 4; ++m) _Pragma("unroll") for (int n = 0; n < 2; ++n) _Pragma("unroll") for (int k = 0; k < 2; ++k) \
;         acc[ai][bj][m][n] = __builtin_amdgcn_mfma_f32_16x16x32_bf16(Bt[n][k], At[m][k], acc[ai][bj][m][n], 0, 0, 0); __builtin_amdgcn_s_setprio(0); } while (0)
; #define PG8_BAR __builtin_amdgcn_s_barrier()
; template <class Epi, bool ALIGN_EPI, bool ABLK = false>
; __device__ __forceinline__ void gemm_phase(PG8_LAS unsigned char* lds, const Gemm g, const StaticOrder& S, const Epi& E) {
;     ...
;     for (;;) {
;         const bool has_next = S.next(ui + 1, nxt);
;         const char* nA = has_next ? PG8_ABASE(nxt) : cA; const char* nB = has_next ? PG8_BBASE(nxt) : cB;
;         for (int t = 0; t < nt; t += 2) {
;             const bool last = (t == nt - 2);
;             const char* a1 = cA + (size_t)(t + 1) * kstepA;
;             const char* a2 = last ? nA : cA + (size_t)(t + 2) * kstepA; const char* b2 = last ? nB : cB + (size_t)(t + 2) * kstepB;
;             const char* a3 = a2 + kstepA; const char* b3 = b2 + kstepB;
;             PG8_LDB(B0, 0, 0); PG8_LDB(B1, 0, 1); PG8_SCHED; PG8_LDA(At, 0, 0); PG8_STAGE(PG8_SA(1, 1), a1 + hstepA, voffA);
;             PG8_WAIT_V(8); PG8_WAIT_L(0); PG8_BAR; PG8_MMA(0, 0, At, B0); PG8_MMA(0, 1, At, B1); PG8_BAR; PG8_SCHED;
;             PG8_LDA(At, 0, 1); PG8_STAGE(PG8_SB(0, 0), b2, voffB); PG8_STAGE(PG8_SB(0, 1), b2 + hstepB, voffB); PG8_STAGE(PG8_SA(0, 0), a2, voffA);
;             PG8_WAIT_V(8); PG8_WAIT_L(0); PG8_BAR; PG8_MMA(1, 0, At, B0); PG8_MMA(1, 1, At, B1); PG8_BAR; PG8_SCHED;
.LBB0_817:
	s_ashr_i32 s57, s56, 31
	s_lshl_b64 s[10:11], s[56:57], 19
	s_add_u32 s58, s74, s10
	s_addc_u32 s59, s75, s11
	s_and_b64 s[10:11], s[8:9], exec
	s_cselect_b32 s33, s59, s39
	s_cselect_b32 s57, s58, s38
	s_ashr_i32 s55, s54, 31
	s_lshl_b64 s[10:11], s[54:55], 19
	s_add_u32 s60, s14, s10
	s_addc_u32 s61, s15, s11
	s_and_b64 s[10:11], s[8:9], exec
	s_cselect_b32 s55, s61, s37
	s_cselect_b32 s62, s60, s36
	s_add_u32 s63, s36, 0x100
	s_addc_u32 s64, s37, 0
	s_mov_b32 s65, -2
	s_mov_b64 s[10:11], 0x10000
	v_add_u32_e32 v248, 0x2000, v154
	v_add_u32_e32 v249, 0x4000, v154
	v_add_u32_e32 v250, 0x6000, v154
	v_add_u32_e32 v251, 0x8000, v154
	v_add_u32_e32 v252, 0xa000, v154
	v_add_u32_e32 v253, 0xc000, v154
	v_add_u32_e32 v152, 0xe000, v154
	v_add_u32_e32 v153, 0x10000, v197
.LBB0_818:
	ds_read_b128 v[132:135], v153
	ds_read_b128 v[136:139], v153 offset:1024
	ds_read_b128 v[140:143], v153 offset:2048
	ds_read_b128 v[144:147], v153 offset:3072
	ds_read_b128 v[148:151], v153 offset:16384
	ds_read_b128 v[178:181], v153 offset:17408
	ds_read_b128 v[182:185], v153 offset:18432
	ds_read_b128 v[212:215], v153 offset:19456
	s_add_u32 s12, s38, s10
	s_addc_u32 s13, s39, s11
	s_sub_u32 s98, s12, 0x10000
	s_subb_u32 s99, s13, 0
	s_cmp_eq_u32 s65, 12
	s_cselect_b32 s101, s33, s13
	s_cselect_b32 s100, s57, s12
	s_cselect_b32 s13, s55, s64
	s_cselect_b32 s12, s62, s63
	s_mov_b64 s[68:69], 0xc000
	s_add_i32 m0, s35, 0xc000
	s_mov_b64 s[68:69], 0xe000
	ds_read_b128 v[216:219], v205
	ds_read_b128 v[220:223], v205 offset:1024
	ds_read_b128 v[224:227], v205 offset:2048
	ds_read_b128 v[228:231], v205 offset:3072
	ds_read_b128 v[232:235], v205 offset:4096
	ds_read_b128 v[236:239], v205 offset:5120
	ds_read_b128 v[240:243], v205 offset:6144
	ds_read_b128 v[244:247], v205 offset:7168
	global_load_lds_dwordx4 v253, s[98:99]
	s_add_i32 m0, s35, 0xe000
	s_nop 0
	global_load_lds_dwordx4 v152, s[98:99]
	s_waitcnt vmcnt(8)
	s_waitcnt lgkmcnt(0)
	s_barrier
	s_setprio 1
	s_waitcnt lgkmcnt(0)
	v_mfma_f32_16x16x32_bf16 v[126:129], v[132:135], v[216:219], v[126:129]
	v_mfma_f32_16x16x32_bf16 v[122:125], v[140:143], v[216:219], v[122:125]
	v_mfma_f32_16x16x32_bf16 v[118:121], v[132:135], v[224:227], v[118:121]
	v_mfma_f32_16x16x32_bf16 v[114:117], v[140:143], v[224:227], v[114:117]
	v_mfma_f32_16x16x32_bf16 v[110:113], v[132:135], v[232:235], v[110:113]
	v_mfma_f32_16x16x32_bf16 v[106:109], v[140:143], v[232:235], v[106:109]
	v_mfma_f32_16x16x32_bf16 v[102:105], v[132:135], v[240:243], v[102:105]
	v_mfma_f32_16x16x32_bf16 v[98:101], v[140:143], v[240:243], v[98:101]
	v_mfma_f32_16x16x32_bf16 v[126:129], v[136:139], v[220:223], v[126:129]
	v_mfma_f32_16x16x32_bf16 v[122:125], v[144:147], v[220:223], v[122:125]
	v_mfma_f32_16x16x32_bf16 v[118:121], v[136:139], v[228:231], v[118:121]
	v_mfma_f32_16x16x32_bf16 v[114:117], v[144:147], v[228:231], v[114:117]
	v_mfma_f32_16x16x32_bf16 v[110:113], v[136:139], v[236:239], v[110:113]
	v_mfma_f32_16x16x32_bf16 v[106:109], v[144:147], v[236:239], v[106:109]
	v_mfma_f32_16x16x32_bf16 v[102:105], v[136:139], v[244:247], v[102:105]
	v_mfma_f32_16x16x32_bf16 v[98:101], v[144:147], v[244:247], v[98:101]
	s_setprio 0
	s_setprio 1
	v_mfma_f32_16x16x32_bf16 v[94:97], v[148:151], v[216:219], v[94:97]
	v_mfma_f32_16x16x32_bf16 v[90:93], v[182:185], v[216:219], v[90:93]
	v_mfma_f32_16x16x32_bf16 v[86:89], v[148:151], v[224:227], v[86:89]
	v_mfma_f32_16x16x32_bf16 v[82:85], v[182:185], v[224:227], v[82:85]
	v_mfma_f32_16x16x32_bf16 v[78:81], v[148:151], v[232:235], v[78:81]
	v_mfma_f32_16x16x32_bf16 v[74:77], v[182:185], v[232:235], v[74:77]
	v_mfma_f32_16x16x32_bf16 v[70:73], v[148:151], v[240:243], v[70:73]
	v_mfma_f32_16x16x32_bf16 v[66:69], v[182:185], v[240:243], v[66:69]
	v_mfma_f32_16x16x32_bf16 v[94:97], v[178:181], v[220:223], v[94:97]
	v_mfma_f32_16x16x32_bf16 v[90:93], v[212:215], v[220:223], v[90:93]
	v_mfma_f32_16x16x32_bf16 v[86:89], v[178:181], v[228:231], v[86:89]
	v_mfma_f32_16x16x32_bf16 v[82:85], v[212:215], v[228:231], v[82:85]
	v_mfma_f32_16x16x32_bf16 v[78:81], v[178:181], v[236:239], v[78:81]
	v_mfma_f32_16x16x32_bf16 v[74:77], v[212:215], v[236:239], v[74:77]
	v_mfma_f32_16x16x32_bf16 v[70:73], v[178:181], v[244:247], v[70:73]
	v_mfma_f32_16x16x32_bf16 v[66:69], v[212:215], v[244:247], v[66:69]
	s_setprio 0
	s_barrier
	s_add_i32 s68, s42, s31
	s_mov_b32 m0, s68
	ds_read_b128 v[216:219], v205 offset:16384
	ds_read_b128 v[220:223], v205 offset:17408
	ds_read_b128 v[224:227], v205 offset:18432
	ds_read_b128 v[228:231], v205 offset:19456
	ds_read_b128 v[232:235], v205 offset:20480
	ds_read_b128 v[236:239], v205 offset:21504
	ds_read_b128 v[240:243], v205 offset:22528
	ds_read_b128 v[244:247], v205 offset:23552
	global_load_lds_dwordx4 v156, s[12:13]
	s_add_i32 m0, s68, 0x2000
	s_add_u32 s68, s12, 0x40000
	s_addc_u32 s69, s13, 0
	s_add_i32 s70, s43, s31
	global_load_lds_dwordx4 v158, s[12:13]
	s_mov_b32 m0, s70
	s_nop 0
	global_load_lds_dwordx4 v156, s[68:69]
	s_add_i32 m0, s70, 0x2000
	s_nop 0
	global_load_lds_dwordx4 v158, s[68:69]
	s_mov_b32 m0, s35
	s_mov_b64 s[66:67], 0x2000
	global_load_lds_dwordx4 v154, s[100:101]
	s_mov_b32 m0, s18
	s_nop 0
	global_load_lds_dwordx4 v248, s[100:101]
	s_waitcnt vmcnt(8)
	s_waitcnt lgkmcnt(0)
	s_barrier
; #define PG8_STAGE(bufoff, gbase, voff) do { _Pragma("unroll") for (int _i = 0; _i < 2; ++_i) \
;         __builtin_amdgcn_global_load_lds((const unsigned*)((const char*)(gbase) + (voff)[_i]), (PG8_LAS unsigned*)(lds + (bufoff) + ldsw + _i * 8192), 16, 0, 0); } while (0)
; #define PG8_LDA(dst, b, h) do { _Pragma("unroll") for (int m = 0; m < 4; ++m) _Pragma("unroll") for (int k = 0; k < 2; ++k) dst[m][k] = *(const PG8_LAS bf16x8*)(lds + PG8_SA(b, h) + aoff + m * 2048 + k * 1024); } while (0)
; #define PG8_LDB(dst, b, h) do { _Pragma("unroll") for (int n = 0; n < 2; ++n) _Pragma("unroll") for (int k = 0; k < 2; ++k) dst[n][k] = *(const PG8_LAS bf16x8*)(lds + PG8_SB(b, h) + boff + n * 2048 + k * 1024); } while (0)
; #define PG8_MMA(ai, bj, At, Bt) do { __builtin_amdgcn_s_setprio(1); _Pragma("unroll") for (int m = 0; m < 4; ++m) _Pragma("unroll") for (int n = 0; n < 2; ++n) _Pragma("unroll") for (int k = 0; k < 2; ++k) \
;         acc[ai][bj][m][n] = __builtin_amdgcn_mfma_f32_16x16x32_bf16(Bt[n][k], At[m][k], acc[ai][bj][m][n], 0, 0, 0); __builtin_amdgcn_s_setprio(0); } while (0)
; #define PG8_WAIT_V(n) asm volatile("s_waitcnt vmcnt(" #n ")" ::: "memory")
; #define PG8_WAIT_L(n) asm volatile("s_waitcnt lgkmcnt(" #n ")" ::: "memory")
; #define PG8_BAR __builtin_amdgcn_s_barrier()
; #define PG8_SCHED __builtin_amdgcn_sched_barrier(0)
; template <class Epi, bool ALIGN_EPI, bool ABLK = false>
; __device__ __forceinline__ void gemm_phase(PG8_LAS unsigned char* lds, const Gemm g, const StaticOrder& S, const Epi& E) {
;     ...
;             PG8_WAIT_V(8); PG8_WAIT_L(0); PG8_BAR; PG8_MMA(1, 0, At, B0); PG8_MMA(1, 1, At, B1); PG8_BAR; PG8_SCHED;
;             PG8_LDB(B0, 1, 0); PG8_LDB(B1, 1, 1); PG8_SCHED; PG8_LDA(At, 1, 0); PG8_STAGE(PG8_SA(0, 1), a2 + hstepA, voffA);
;             PG8_WAIT_V(8); PG8_WAIT_L(0); PG8_BAR; PG8_MMA(0, 0, At, B0); PG8_MMA(0, 1, At, B1); PG8_BAR; PG8_SCHED;
	s_setprio 1
	s_waitcnt lgkmcnt(0)
	v_mfma_f32_16x16x32_bf16 v[62:65], v[132:135], v[216:219], v[62:65]
	v_mfma_f32_16x16x32_bf16 v[58:61], v[140:143], v[216:219], v[58:61]
	v_mfma_f32_16x16x32_bf16 v[54:57], v[132:135], v[224:227], v[54:57]
	v_mfma_f32_16x16x32_bf16 v[50:53], v[140:143], v[224:227], v[50:53]
	v_mfma_f32_16x16x32_bf16 v[46:49], v[132:135], v[232:235], v[46:49]
	v_mfma_f32_16x16x32_bf16 v[42:45], v[140:143], v[232:235], v[42:45]
	v_mfma_f32_16x16x32_bf16 v[38:41], v[132:135], v[240:243], v[38:41]
	v_mfma_f32_16x16x32_bf16 v[34:37], v[140:143], v[240:243], v[34:37]
	v_mfma_f32_16x16x32_bf16 v[62:65], v[136:139], v[220:223], v[62:65]
	v_mfma_f32_16x16x32_bf16 v[58:61], v[144:147], v[220:223], v[58:61]
	v_mfma_f32_16x16x32_bf16 v[54:57], v[136:139], v[228:231], v[54:57]
	v_mfma_f32_16x16x32_bf16 v[50:53], v[144:147], v[228:231], v[50:53]
	v_mfma_f32_16x16x32_bf16 v[46:49], v[136:139], v[236:239], v[46:49]
	v_mfma_f32_16x16x32_bf16 v[42:45], v[144:147], v[236:239], v[42:45]
	v_mfma_f32_16x16x32_bf16 v[38:41], v[136:139], v[244:247], v[38:41]
	v_mfma_f32_16x16x32_bf16 v[34:37], v[144:147], v[244:247], v[34:37]
	s_setprio 0
	s_setprio 1
	v_mfma_f32_16x16x32_bf16 v[30:33], v[148:151], v[216:219], v[30:33]
	v_mfma_f32_16x16x32_bf16 v[26:29], v[182:185], v[216:219], v[26:29]
	v_mfma_f32_16x16x32_bf16 v[22:25], v[148:151], v[224:227], v[22:25]
	v_mfma_f32_16x16x32_bf16 v[18:21], v[182:185], v[224:227], v[18:21]
	v_mfma_f32_16x16x32_bf16 v[14:17], v[148:151], v[232:235], v[14:17]
	v_mfma_f32_16x16x32_bf16 v[10:13], v[182:185], v[232:235], v[10:13]
	v_mfma_f32_16x16x32_bf16 v[6:9], v[148:151], v[240:243], v[6:9]
	v_mfma_f32_16x16x32_bf16 v[2:5], v[182:185], v[240:243], v[2:5]
	v_mfma_f32_16x16x32_bf16 v[30:33], v[178:181], v[220:223], v[30:33]
	v_mfma_f32_16x16x32_bf16 v[26:29], v[212:215], v[220:223], v[26:29]
	v_mfma_f32_16x16x32_bf16 v[22:25], v[178:181], v[228:231], v[22:25]
	v_mfma_f32_16x16x32_bf16 v[18:21], v[212:215], v[228:231], v[18:21]
	v_mfma_f32_16x16x32_bf16 v[14:17], v[178:181], v[236:239], v[14:17]
	v_mfma_f32_16x16x32_bf16 v[10:13], v[212:215], v[236:239], v[10:13]
	v_mfma_f32_16x16x32_bf16 v[6:9], v[178:181], v[244:247], v[6:9]
	v_mfma_f32_16x16x32_bf16 v[2:5], v[212:215], v[244:247], v[2:5]
	s_setprio 0
	s_barrier
	s_add_i32 s68, 0, 0x18000
	s_add_i32 s69, 0, 0x1c000
	ds_read_b128 v[132:135], v153 offset:32768
	ds_read_b128 v[136:139], v153 offset:33792
	ds_read_b128 v[140:143], v153 offset:34816
	ds_read_b128 v[144:147], v153 offset:35840
	ds_read_b128 v[148:151], v153 offset:49152
	ds_read_b128 v[178:181], v153 offset:50176
	ds_read_b128 v[182:185], v153 offset:51200
	ds_read_b128 v[212:215], v153 offset:52224
	s_mov_b64 s[66:67], 0x4000
	s_mov_b32 m0, s28
	s_mov_b64 s[66:67], 0x6000
	ds_read_b128 v[216:219], v205 offset:32768
	ds_read_b128 v[220:223], v205 offset:33792
	ds_read_b128 v[224:227], v205 offset:34816
	ds_read_b128 v[228:231], v205 offset:35840
	ds_read_b128 v[232:235], v205 offset:36864
	ds_read_b128 v[236:239], v205 offset:37888
	ds_read_b128 v[240:243], v205 offset:38912
	ds_read_b128 v[244:247], v205 offset:39936
	global_load_lds_dwordx4 v249, s[100:101]
	s_mov_b32 m0, s29
	s_nop 0
	global_load_lds_dwordx4 v250, s[100:101]
	s_waitcnt vmcnt(8)
	s_waitcnt lgkmcnt(0)
	s_barrier
	s_setprio 1
	s_waitcnt lgkmcnt(0)
	v_mfma_f32_16x16x32_bf16 v[126:129], v[132:135], v[216:219], v[126:129]
	v_mfma_f32_16x16x32_bf16 v[122:125], v[140:143], v[216:219], v[122:125]
	v_mfma_f32_16x16x32_bf16 v[118:121], v[132:135], v[224:227], v[118:121]
	v_mfma_f32_16x16x32_bf16 v[114:117], v[140:143], v[224:227], v[114:117]
	v_mfma_f32_16x16x32_bf16 v[110:113], v[132:135], v[232:235], v[110:113]
	v_mfma_f32_16x16x32_bf16 v[106:109], v[140:143], v[232:235], v[106:109]
	v_mfma_f32_16x16x32_bf16 v[102:105], v[132:135], v[240:243], v[102:105]
	v_mfma_f32_16x16x32_bf16 v[98:101], v[140:143], v[240:243], v[98:101]
	v_mfma_f32_16x16x32_bf16 v[126:129], v[136:139], v[220:223], v[126:129]
	v_mfma_f32_16x16x32_bf16 v[122:125], v[144:147], v[220:223], v[122:125]
	v_mfma_f32_16x16x32_bf16 v[118:121], v[136:139], v[228:231], v[118:121]
	v_mfma_f32_16x16x32_bf16 v[114:117], v[144:147], v[228:231], v[114:117]
	v_mfma_f32_16x16x32_bf16 v[110:113], v[136:139], v[236:239], v[110:113]
	v_mfma_f32_16x16x32_bf16 v[106:109], v[144:147], v[236:239], v[106:109]
	v_mfma_f32_16x16x32_bf16 v[102:105], v[136:139], v[244:247], v[102:105]
	v_mfma_f32_16x16x32_bf16 v[98:101], v[144:147], v[244:247], v[98:101]
	s_setprio 0
	s_setprio 1
	v_mfma_f32_16x16x32_bf16 v[94:97], v[148:151], v[216:219], v[94:97]
	v_mfma_f32_16x16x32_bf16 v[90:93], v[182:185], v[216:219], v[90:93]
	v_mfma_f32_16x16x32_bf16 v[86:89], v[148:151], v[224:227], v[86:89]
	v_mfma_f32_16x16x32_bf16 v[82:85], v[182:185], v[224:227], v[82:85]
	v_mfma_f32_16x16x32_bf16 v[78:81], v[148:151], v[232:235], v[78:81]
	v_mfma_f32_16x16x32_bf16 v[74:77], v[182:185], v[232:235], v[74:77]
	v_mfma_f32_16x16x32_bf16 v[70:73], v[148:151], v[240:243], v[70:73]
	v_mfma_f32_16x16x32_bf16 v[66:69], v[182:185], v[240:243], v[66:69]
	v_mfma_f32_16x16x32_bf16 v[94:97], v[178:181], v[220:223], v[94:97]
	v_mfma_f32_16x16x32_bf16 v[90:93], v[212:215], v[220:223], v[90:93]
	v_mfma_f32_16x16x32_bf16 v[86:89], v[178:181], v[228:231], v[86:89]
	v_mfma_f32_16x16x32_bf16 v[82:85], v[212:215], v[228:231], v[82:85]
	v_mfma_f32_16x16x32_bf16 v[78:81], v[178:181], v[236:239], v[78:81]
	v_mfma_f32_16x16x32_bf16 v[74:77], v[212:215], v[236:239], v[74:77]
	v_mfma_f32_16x16x32_bf16 v[70:73], v[178:181], v[244:247], v[70:73]
	v_mfma_f32_16x16x32_bf16 v[66:69], v[212:215], v[244:247], v[66:69]
	s_setprio 0
	s_barrier
; #define PG8_STAGE(bufoff, gbase, voff) do { _Pragma("unroll") for (int _i = 0; _i < 2; ++_i) \
;         __builtin_amdgcn_global_load_lds((const unsigned*)((const char*)(gbase) + (voff)[_i]), (PG8_LAS unsigned*)(lds + (bufoff) + ldsw + _i * 8192), 16, 0, 0); } while (0)
; #define PG8_LDA(dst, b, h) do { _Pragma("unroll") for (int m = 0; m < 4; ++m) _Pragma("unroll") for (int k = 0; k < 2; ++k) dst[m][k] = *(const PG8_LAS bf16x8*)(lds + PG8_SA(b, h) + aoff + m * 2048 + k * 1024); } while (0)
; #define PG8_MMA(ai, bj, At, Bt) do { __builtin_amdgcn_s_setprio(1); _Pragma("unroll") for (int m = 0; m < 4; ++m) _Pragma("unroll") for (int n = 0; n < 2; ++n) _Pragma("unroll") for (int k = 0; k < 2; ++k) \
;         acc[ai][bj][m][n] = __builtin_amdgcn_mfma_f32_16x16x32_bf16(Bt[n][k], At[m][k], acc[ai][bj][m][n], 0, 0, 0); __builtin_amdgcn_s_setprio(0); } while (0)
; #define PG8_WAIT_V(n) asm volatile("s_waitcnt vmcnt(" #n ")" ::: "memory")
; #define PG8_WAIT_L(n) asm volatile("s_waitcnt lgkmcnt(" #n ")" ::: "memory")
; #define PG8_BAR __builtin_amdgcn_s_barrier()
; #define PG8_SCHED __builtin_amdgcn_sched_barrier(0)
; template <class Epi, bool ALIGN_EPI, bool ABLK = false>
; __device__ __forceinline__ void gemm_phase(PG8_LAS unsigned char* lds, const Gemm g, const StaticOrder& S, const Epi& E) {
;     ...
;         for (int t = 0; t < nt; t += 2) {
;     ...
;             PG8_LDA(At, 1, 1); PG8_STAGE(PG8_SB(1, 0), b3, voffB); PG8_STAGE(PG8_SB(1, 1), b3 + hstepB, voffB); PG8_STAGE(PG8_SA(1, 0), a3, voffA);
;             PG8_WAIT_V(8); PG8_WAIT_L(0); PG8_BAR; PG8_MMA(1, 0, At, B0); PG8_MMA(1, 1, At, B1); PG8_BAR; PG8_SCHED;
;         }
	s_add_i32 s66, s68, s31
	s_add_u32 s12, s12, s46
	s_addc_u32 s13, s13, s47
	s_mov_b32 m0, s66
	ds_read_b128 v[216:219], v205 offset:49152
	ds_read_b128 v[220:223], v205 offset:50176
	ds_read_b128 v[224:227], v205 offset:51200
	ds_read_b128 v[228:231], v205 offset:52224
	ds_read_b128 v[232:235], v205 offset:53248
	ds_read_b128 v[236:239], v205 offset:54272
	ds_read_b128 v[240:243], v205 offset:55296
	ds_read_b128 v[244:247], v205 offset:56320
	global_load_lds_dwordx4 v156, s[12:13]
	s_add_i32 m0, s66, 0x2000
	s_add_i32 s66, s69, s31
	global_load_lds_dwordx4 v158, s[12:13]
	s_add_u32 s12, s12, 0x40000
	s_addc_u32 s13, s13, 0
	s_mov_b32 m0, s66
	s_nop 0
	global_load_lds_dwordx4 v156, s[12:13]
	s_add_i32 m0, s66, 0x2000
	s_nop 0
	global_load_lds_dwordx4 v158, s[12:13]
	s_mov_b32 m0, s0
	s_nop 0
	global_load_lds_dwordx4 v251, s[100:101]
	s_mov_b32 m0, s1
	s_nop 0
	global_load_lds_dwordx4 v252, s[100:101]
	s_waitcnt vmcnt(8)
	s_waitcnt lgkmcnt(0)
	s_barrier
	s_setprio 1
	s_waitcnt lgkmcnt(0)
	v_mfma_f32_16x16x32_bf16 v[62:65], v[132:135], v[216:219], v[62:65]
	v_mfma_f32_16x16x32_bf16 v[58:61], v[140:143], v[216:219], v[58:61]
	v_mfma_f32_16x16x32_bf16 v[54:57], v[132:135], v[224:227], v[54:57]
	v_mfma_f32_16x16x32_bf16 v[50:53], v[140:143], v[224:227], v[50:53]
	v_mfma_f32_16x16x32_bf16 v[46:49], v[132:135], v[232:235], v[46:49]
	v_mfma_f32_16x16x32_bf16 v[42:45], v[140:143], v[232:235], v[42:45]
	v_mfma_f32_16x16x32_bf16 v[38:41], v[132:135], v[240:243], v[38:41]
	v_mfma_f32_16x16x32_bf16 v[34:37], v[140:143], v[240:243], v[34:37]
	v_mfma_f32_16x16x32_bf16 v[62:65], v[136:139], v[220:223], v[62:65]
	v_mfma_f32_16x16x32_bf16 v[58:61], v[144:147], v[220:223], v[58:61]
	v_mfma_f32_16x16x32_bf16 v[54:57], v[136:139], v[228:231], v[54:57]
	v_mfma_f32_16x16x32_bf16 v[50:53], v[144:147], v[228:231], v[50:53]
	v_mfma_f32_16x16x32_bf16 v[46:49], v[136:139], v[236:239], v[46:49]
	v_mfma_f32_16x16x32_bf16 v[42:45], v[144:147], v[236:239], v[42:45]
	v_mfma_f32_16x16x32_bf16 v[38:41], v[136:139], v[244:247], v[38:41]
	v_mfma_f32_16x16x32_bf16 v[34:37], v[144:147], v[244:247], v[34:37]
	s_setprio 0
	s_setprio 1
	v_mfma_f32_16x16x32_bf16 v[30:33], v[148:151], v[216:219], v[30:33]
	v_mfma_f32_16x16x32_bf16 v[26:29], v[182:185], v[216:219], v[26:29]
	v_mfma_f32_16x16x32_bf16 v[22:25], v[148:151], v[224:227], v[22:25]
	v_mfma_f32_16x16x32_bf16 v[18:21], v[182:185], v[224:227], v[18:21]
	v_mfma_f32_16x16x32_bf16 v[14:17], v[148:151], v[232:235], v[14:17]
	v_mfma_f32_16x16x32_bf16 v[10:13], v[182:185], v[232:235], v[10:13]
	v_mfma_f32_16x16x32_bf16 v[6:9], v[148:151], v[240:243], v[6:9]
	v_mfma_f32_16x16x32_bf16 v[2:5], v[182:185], v[240:243], v[2:5]
	v_mfma_f32_16x16x32_bf16 v[30:33], v[178:181], v[220:223], v[30:33]
	v_mfma_f32_16x16x32_bf16 v[26:29], v[212:215], v[220:223], v[26:29]
	v_mfma_f32_16x16x32_bf16 v[22:25], v[178:181], v[228:231], v[22:25]
	v_mfma_f32_16x16x32_bf16 v[18:21], v[212:215], v[228:231], v[18:21]
	v_mfma_f32_16x16x32_bf16 v[14:17], v[178:181], v[236:239], v[14:17]
	v_mfma_f32_16x16x32_bf16 v[10:13], v[212:215], v[236:239], v[10:13]
	v_mfma_f32_16x16x32_bf16 v[6:9], v[178:181], v[244:247], v[6:9]
	v_mfma_f32_16x16x32_bf16 v[2:5], v[212:215], v[244:247], v[2:5]
	s_setprio 0
	s_barrier
	s_add_i32 s65, s65, 2
	s_add_u32 s63, s63, 0x100
	s_addc_u32 s64, s64, 0
	s_add_u32 s10, s10, 0x10000
	s_addc_u32 s11, s11, 0
	s_mov_b64 s[12:13], 0x10000
	s_cmp_gt_u32 s65, 13
	s_cbranch_scc0 .LBB0_818
	s_and_b64 vcc, exec, s[52:53]
	s_cbranch_vccz .LBB0_821
	s_barrier

; #define PG8_LAS __attribute__((address_space(3)))
; #define PG8_WAIT_V(n) asm volatile("s_waitcnt vmcnt(" #n ")" ::: "memory")
; #define PG8_BAR __builtin_amdgcn_s_barrier()
; #define S xcd_barrier(bar);
; template <class Epi, bool ALIGN_EPI, bool ABLK = false>
; __device__ __forceinline__ void gemm_phase(PG8_LAS unsigned char* lds, const Gemm g, const StaticOrder& S, const Epi& E) {
;     ...
;     const unsigned ldsw = (unsigned)wid * 1024u;
;     const int aoff = lds_byte(wr * 64 + fr, fq * 8), boff = lds_byte(wc * 32 + fr, fq * 8);
;     ...
;     Unit cur, nxt; int ui = 0;
;     if (!S.next(0, cur)) return;
;     Acc acc;
; #pragma unroll
;     for (int a = 0; a < 2; ++a)
; #pragma unroll
;         for (int b = 0; b < 2; ++b)
; #pragma unroll
;             for (int m = 0; m < 4; ++m)
; #pragma unroll
;                 for (int n = 0; n < 2; ++n) acc[a][b][m][n] = (f32x4){0.f, 0.f, 0.f, 0.f};
;     bf16x8 At[4][2], B0[2][2], B1[2][2];
;     const char* cA = PG8_ABASE(cur); const char* cB = PG8_BBASE(cur);
;     constexpr int RS_MAXT = 12;
;     PG8_LAS float* RS = (PG8_LAS float*)(lds + EX_OFF);
;     f32x4 rq[RS_MAXT][2];
;     if constexpr (Epi::RSTD_LDS) {
; #pragma unroll
;         for (int i = 0; i < RS_MAXT; ++i) { Unit t; if (S.next(i, t)) { const float* p = E.ssqp + (size_t)(t.pm * BM + wid * 32 + (lane & 31)) * 16 + (lane >> 5) * 8; rq[i][0] = *(const f32x4*)p; rq[i][1] = *(const f32x4*)(p + 4); } }
;     }
;     PG8_STAGE(PG8_SB(0, 0), cB, voffB); PG8_STAGE(PG8_SB(0, 1), cB + hstepB, voffB); PG8_STAGE(PG8_SA(0, 0), cA, voffA); PG8_STAGE(PG8_SA(0, 1), cA + hstepA, voffA);
;     if constexpr (Epi::RSTD_LDS) {
;         const int prow = wid * 32 + (lane & 31), slot = (((prow >> 6) & 1) * 16 + (prow & 15)) * 8 + (prow >> 7) * 4 + ((prow >> 4) & 3);
; #pragma unroll
;         for (int i = 0; i < RS_MAXT; ++i) { Unit t; if (S.next(i, t)) {
;             float sm = ((rq[i][0].x + rq[i][0].y) + (rq[i][0].z + rq[i][0].w)) + ((rq[i][1].x + rq[i][1].y) + (rq[i][1].z + rq[i][1].w));
;             sm += __shfl_xor(sm, 32);
;             if (lane < 32) RS[i * 256 + slot] = __builtin_amdgcn_rsqf(sm * (1.0f / D) + EPS); } }
;     }
;     if (wr == 1) PG8_BAR;
;     PG8_WAIT_V(2); PG8_BAR;
;     PG8_STAGE(PG8_SB(1, 0), cB + kstepB, voffB); PG8_STAGE(PG8_SA(1, 0), cA + kstepA, voffA); PG8_STAGE(PG8_SB(1, 1), cB + hstepB + kstepB, voffB);
;     PG8_WAIT_V(6); PG8_BAR;
.LBB0_2489:
	s_and_b32 s5, s30, 3
	v_and_b32_e32 v8, 15, v0
	v_and_b32_e32 v9, 48, v0
	v_lshlrev_b32_e32 v11, 2, v0
	v_lshlrev_b32_e32 v13, 6, v0
	s_movk_i32 s29, 0x3c0
	v_lshl_or_b32 v10, v8, 6, v9
	v_and_b32_e32 v11, 32, v11
	s_lshl_b32 s28, s5, 12
	v_and_or_b32 v9, v13, s29, v9
	v_bitop3_b32 v173, s28, v9, v11 bitop3:0xf6
	s_mov_b64 s[28:29], 0x80
	s_add_i32 m0, s66, 0x18000
	v_lshl_add_u64 v[2:3], v[2:3], 0, s[28:29]
	s_lshl_b32 s39, s4, 13
	s_lshl_b32 s17, s5, 5
	s_waitcnt vmcnt(2)
	s_barrier
	global_load_lds_dwordx4 v[2:3], off
	v_lshl_add_u64 v[2:3], v[4:5], 0, s[28:29]
	s_add_i32 m0, s66, 0x1a000
	s_mov_b64 s[30:31], 0x8000
	s_add_i32 s70, s66, 0x8000
	s_add_i32 s72, s66, 0xa000
	global_load_lds_dwordx4 v[2:3], off
	v_lshl_add_u64 v[2:3], v[100:101], 0, s[30:31]
	s_mov_b32 m0, s70
	s_mov_b64 s[34:35], 0xa000
	s_add_u32 s36, s22, 0x40080
	global_load_lds_dwordx4 v[2:3], off
	v_lshl_add_u64 v[2:3], v[100:101], 0, s[34:35]
	s_mov_b32 m0, s72
	s_addc_u32 s37, s23, 0
	global_load_lds_dwordx4 v[2:3], off
	s_add_i32 m0, s66, 0x1c000
	v_lshl_add_u64 v[2:3], s[36:37], 0, v[140:141]
	global_load_lds_dwordx4 v[2:3], off
	v_lshl_add_u64 v[2:3], s[36:37], 0, v[142:143]
	s_add_i32 m0, s66, 0x1e000
	s_cmpk_lt_u32 s38, 0x100
	global_load_lds_dwordx4 v[2:3], off
	v_and_b32_e32 v2, 12, v99
	v_lshlrev_b32_e32 v144, 2, v2
	v_mov_b32_e32 v145, 0
	s_cselect_b64 s[36:37], -1, 0
	v_lshl_add_u64 v[146:147], s[6:7], 0, v[144:145]
	s_lshl_b32 s6, s4, 9
	s_add_i32 s6, s6, 0
	v_lshl_or_b32 v172, s4, 6, v8
	s_add_i32 s6, s6, 0x20000
	s_lshl_b32 s4, s4, 3
	v_lshl_add_u32 v174, v8, 5, s6
	s_bfe_u32 s6, s38, 0x10006
	s_and_b32 s4, s4, 8
	s_or_b32 s6, s4, s6
	s_or_b32 s4, s4, s5
	s_lshl_b32 s4, s4, 10
	v_bitop3_b32 v2, v10, s4, v11 bitop3:0xde
	v_or_b32_e32 v148, 0x800, v2
	v_or_b32_e32 v152, 0x1800, v2
	v_xor_b32_e32 v2, 16, v6
	s_waitcnt vmcnt(6)
	s_lshl_b32 s6, s6, 10
	v_cmp_lt_i32_e32 vcc, v2, v7
	v_bitop3_b32 v12, v10, s39, v11 bitop3:0xde
	s_and_b32 s73, s39, 0x4000
	v_bitop3_b32 v144, v10, s6, v11 bitop3:0xde
	v_cndmask_b32_e32 v2, v6, v2, vcc
	s_mov_b32 s71, 0
	v_mov_b32_e32 v149, v145
	v_or_b32_e32 v150, 0x1000, v144
	v_mov_b32_e32 v151, v145
	v_mov_b32_e32 v153, v145
	s_xor_b32 s74, s73, 0x4000
	v_lshlrev_b32_e32 v175, 2, v2
	v_mov_b64_e32 v[154:155], 0xb00
	v_mov_b64_e32 v[156:157], 0xaff
	s_add_i32 s75, 0, 0x10000
	s_add_i32 s76, 0, 0x14000
	v_add_u32_e32 v176, 0, v12
	s_mov_b64 s[38:39], 0xc000
	s_mov_b64 s[40:41], 0xe000
	s_movk_i32 s77, 0x2000
	s_mov_b64 s[42:43], 0x2000
	s_mov_b64 s[44:45], 0x4000
	s_mov_b64 s[46:47], 0x6000
	s_mov_b64 s[48:49], 0x10000
	v_mov_b32_e32 v177, 0x358637bd
	v_mov_b32_e32 v2, v145
	v_mov_b32_e32 v3, v145
	v_mov_b32_e32 v4, v145
	v_mov_b32_e32 v5, v145
	v_mov_b32_e32 v6, v145
	v_mov_b32_e32 v7, v145
	v_mov_b32_e32 v8, v145
	v_mov_b32_e32 v9, v145
	v_mov_b32_e32 v10, v145
	v_mov_b32_e32 v11, v145
	v_mov_b32_e32 v12, v145
	v_mov_b32_e32 v13, v145
	v_mov_b32_e32 v14, v145
	v_mov_b32_e32 v15, v145
	v_mov_b32_e32 v16, v145
	v_mov_b32_e32 v17, v145
	v_mov_b32_e32 v18, v145
	v_mov_b32_e32 v19, v145
	v_mov_b32_e32 v20, v145
	v_mov_b32_e32 v21, v145
	v_mov_b32_e32 v22, v145
	v_mov_b32_e32 v23, v145
	v_mov_b32_e32 v24, v145
	v_mov_b32_e32 v25, v145
	v_mov_b32_e32 v26, v145
	v_mov_b32_e32 v27, v145
	v_mov_b32_e32 v28, v145
	v_mov_b32_e32 v29, v145
	v_mov_b32_e32 v30, v145
	v_mov_b32_e32 v31, v145
	v_mov_b32_e32 v32, v145
	v_mov_b32_e32 v33, v145
	v_mov_b32_e32 v34, v145
	v_mov_b32_e32 v35, v145
	v_mov_b32_e32 v36, v145
	v_mov_b32_e32 v37, v145
	v_mov_b32_e32 v38, v145
	v_mov_b32_e32 v39, v145
	v_mov_b32_e32 v40, v145
	v_mov_b32_e32 v41, v145
	v_mov_b32_e32 v42, v145
	v_mov_b32_e32 v43, v145
	v_mov_b32_e32 v44, v145
	v_mov_b32_e32 v45, v145
	v_mov_b32_e32 v46, v145
	v_mov_b32_e32 v47, v145
	v_mov_b32_e32 v48, v145
	v_mov_b32_e32 v49, v145
	v_mov_b32_e32 v50, v145
	v_mov_b32_e32 v51, v145
	v_mov_b32_e32 v52, v145
	v_mov_b32_e32 v53, v145
	v_mov_b32_e32 v54, v145
	v_mov_b32_e32 v55, v145
	v_mov_b32_e32 v56, v145
	v_mov_b32_e32 v57, v145
	v_mov_b32_e32 v58, v145
	v_mov_b32_e32 v59, v145
	v_mov_b32_e32 v60, v145
	v_mov_b32_e32 v61, v145
	v_mov_b32_e32 v62, v145
	v_mov_b32_e32 v63, v145
	v_mov_b32_e32 v64, v145
	v_mov_b32_e32 v65, v145
	v_mov_b32_e32 v66, v145
	v_mov_b32_e32 v67, v145
	v_mov_b32_e32 v68, v145
	v_mov_b32_e32 v69, v145
	v_mov_b32_e32 v70, v145
	v_mov_b32_e32 v71, v145
	v_mov_b32_e32 v72, v145
	v_mov_b32_e32 v73, v145
	v_mov_b32_e32 v74, v145
	v_mov_b32_e32 v75, v145
	v_mov_b32_e32 v76, v145
	v_mov_b32_e32 v77, v145
	v_mov_b32_e32 v78, v145
	v_mov_b32_e32 v79, v145
	v_mov_b32_e32 v80, v145
	v_mov_b32_e32 v81, v145
	v_mov_b32_e32 v82, v145
	v_mov_b32_e32 v83, v145
	v_mov_b32_e32 v84, v145
	v_mov_b32_e32 v85, v145
	v_mov_b32_e32 v86, v145
	v_mov_b32_e32 v87, v145
	v_mov_b32_e32 v88, v145
	v_mov_b32_e32 v89, v145
	v_mov_b32_e32 v90, v145
	v_mov_b32_e32 v91, v145
	v_mov_b32_e32 v92, v145
	v_mov_b32_e32 v93, v145
	v_mov_b32_e32 v94, v145
	v_mov_b32_e32 v95, v145
	v_mov_b32_e32 v96, v145
	v_mov_b32_e32 v97, v145
	v_mov_b32_e32 v98, v145
	v_mov_b32_e32 v99, v145
	v_mov_b32_e32 v100, v145
	v_mov_b32_e32 v101, v145
	v_mov_b32_e32 v102, v145
	v_mov_b32_e32 v103, v145
	v_mov_b32_e32 v104, v145
	v_mov_b32_e32 v105, v145
	v_mov_b32_e32 v106, v145
	v_mov_b32_e32 v107, v145
	v_mov_b32_e32 v108, v145
	v_mov_b32_e32 v109, v145
	v_mov_b32_e32 v110, v145
	v_mov_b32_e32 v111, v145
	v_mov_b32_e32 v112, v145
	v_mov_b32_e32 v113, v145
	v_mov_b32_e32 v114, v145
	v_mov_b32_e32 v115, v145
	v_mov_b32_e32 v116, v145
	v_mov_b32_e32 v117, v145
	v_mov_b32_e32 v118, v145
	v_mov_b32_e32 v119, v145
	v_mov_b32_e32 v120, v145
	v_mov_b32_e32 v121, v145
	v_mov_b32_e32 v122, v145
	v_mov_b32_e32 v123, v145
	v_mov_b32_e32 v124, v145
	v_mov_b32_e32 v125, v145
	v_mov_b32_e32 v126, v145
	v_mov_b32_e32 v127, v145
	v_mov_b32_e32 v128, v145
	v_mov_b32_e32 v129, v145
	v_add_u32_e32 v244, 0x2000, v138
	v_add_u32_e32 v245, 0x4000, v138
	v_add_u32_e32 v246, 0x6000, v138
	v_add_u32_e32 v247, 0x8000, v138
	v_add_u32_e32 v248, 0xa000, v138
	v_add_u32_e32 v249, 0xc000, v138
	v_add_u32_e32 v250, 0xe000, v138
	v_add_u32_e32 v251, 0x10000, v173
	s_barrier
	s_branch .LBB0_2492

; #define PG8_STAGE(bufoff, gbase, voff) do { _Pragma("unroll") for (int _i = 0; _i < 2; ++_i) \
;         __builtin_amdgcn_global_load_lds((const unsigned*)((const char*)(gbase) + (voff)[_i]), (PG8_LAS unsigned*)(lds + (bufoff) + ldsw + _i * 8192), 16, 0, 0); } while (0)
; #define PG8_LDA(dst, b, h) do { _Pragma("unroll") for (int m = 0; m < 4; ++m) _Pragma("unroll") for (int k = 0; k < 2; ++k) dst[m][k] = *(const PG8_LAS bf16x8*)(lds + PG8_SA(b, h) + aoff + m * 2048 + k * 1024); } while (0)
; #define PG8_LDB(dst, b, h) do { _Pragma("unroll") for (int n = 0; n < 2; ++n) _Pragma("unroll") for (int k = 0; k < 2; ++k) dst[n][k] = *(const PG8_LAS bf16x8*)(lds + PG8_SB(b, h) + boff + n * 2048 + k * 1024); } while (0)
; #define PG8_MMA(ai, bj, At, Bt) do { __builtin_amdgcn_s_setprio(1); _Pragma("unroll") for (int m = 0; m < 4; ++m) _Pragma("unroll") for (int n = 0; n < 2; ++n) _Pragma("unroll") for (int k = 0; k < 2; ++k) \
;         acc[ai][bj][m][n] = __builtin_amdgcn_mfma_f32_16x16x32_bf16(Bt[n][k], At[m][k], acc[ai][bj][m][n], 0, 0, 0); __builtin_amdgcn_s_setprio(0); } while (0)
; #define PG8_BAR __builtin_amdgcn_s_barrier()
; template <class Epi, bool ALIGN_EPI, bool ABLK = false>
; __device__ __forceinline__ void gemm_phase(PG8_LAS unsigned char* lds, const Gemm g, const StaticOrder& S, const Epi& E) {
;     ...
;     for (;;) {
;         const bool has_next = S.next(ui + 1, nxt);
;         const char* nA = has_next ? PG8_ABASE(nxt) : cA; const char* nB = has_next ? PG8_BBASE(nxt) : cB;
;         for (int t = 0; t < nt; t += 2) {
;             const bool last = (t == nt - 2);
;             const char* a1 = cA + (size_t)(t + 1) * kstepA;
;             const char* a2 = last ? nA : cA + (size_t)(t + 2) * kstepA; const char* b2 = last ? nB : cB + (size_t)(t + 2) * kstepB;
;             const char* a3 = a2 + kstepA; const char* b3 = b2 + kstepB;
;             PG8_LDB(B0, 0, 0); PG8_LDB(B1, 0, 1); PG8_SCHED; PG8_LDA(At, 0, 0); PG8_STAGE(PG8_SA(1, 1), a1 + hstepA, voffA);
;             PG8_WAIT_V(8); PG8_WAIT_L(0); PG8_BAR; PG8_MMA(0, 0, At, B0); PG8_MMA(0, 1, At, B1); PG8_BAR; PG8_SCHED;
;             PG8_LDA(At, 0, 1); PG8_STAGE(PG8_SB(0, 0), b2, voffB); PG8_STAGE(PG8_SB(0, 1), b2 + hstepB, voffB); PG8_STAGE(PG8_SA(0, 0), a2, voffA);
;             PG8_WAIT_V(8); PG8_WAIT_L(0); PG8_BAR; PG8_MMA(1, 0, At, B0); PG8_MMA(1, 1, At, B1); PG8_BAR; PG8_SCHED;
.LBB0_2495:
	ds_read_b128 v[132:135], v251
	ds_read_b128 v[178:181], v251 offset:1024
	ds_read_b128 v[182:185], v251 offset:2048
	ds_read_b128 v[186:189], v251 offset:3072
	ds_read_b128 v[190:193], v251 offset:16384
	ds_read_b128 v[194:197], v251 offset:17408
	ds_read_b128 v[198:201], v251 offset:18432
	ds_read_b128 v[202:205], v251 offset:19456
	s_add_u32 s60, s24, s58
	s_addc_u32 s61, s25, s59
	s_sub_u32 s98, s60, 0x10000
	s_subb_u32 s99, s61, 0
	s_cmp_eq_u32 s83, 12
	s_cselect_b32 s101, s53, s61
	s_cselect_b32 s100, s79, s60
	s_cselect_b32 s61, s51, s82
	s_cselect_b32 s60, s80, s81
	s_add_i32 m0, s66, 0xc000
	ds_read_b128 v[206:209], v176
	ds_read_b128 v[210:213], v176 offset:1024
	ds_read_b128 v[214:217], v176 offset:2048
	ds_read_b128 v[218:221], v176 offset:3072
	ds_read_b128 v[222:225], v176 offset:4096
	ds_read_b128 v[226:229], v176 offset:5120
	ds_read_b128 v[230:233], v176 offset:6144
	ds_read_b128 v[234:237], v176 offset:7168
	global_load_lds_dwordx4 v249, s[98:99]
	s_add_i32 m0, s66, 0xe000
	s_nop 0
	global_load_lds_dwordx4 v250, s[98:99]
	s_waitcnt vmcnt(8)
	s_waitcnt lgkmcnt(0)
	s_barrier
	s_setprio 1
	s_waitcnt lgkmcnt(0)
	v_mfma_f32_16x16x32_bf16 v[126:129], v[132:135], v[206:209], v[126:129]
	v_mfma_f32_16x16x32_bf16 v[122:125], v[182:185], v[206:209], v[122:125]
	v_mfma_f32_16x16x32_bf16 v[118:121], v[132:135], v[214:217], v[118:121]
	v_mfma_f32_16x16x32_bf16 v[114:117], v[182:185], v[214:217], v[114:117]
	v_mfma_f32_16x16x32_bf16 v[110:113], v[132:135], v[222:225], v[110:113]
	v_mfma_f32_16x16x32_bf16 v[106:109], v[182:185], v[222:225], v[106:109]
	v_mfma_f32_16x16x32_bf16 v[102:105], v[132:135], v[230:233], v[102:105]
	v_mfma_f32_16x16x32_bf16 v[98:101], v[182:185], v[230:233], v[98:101]
	v_mfma_f32_16x16x32_bf16 v[126:129], v[178:181], v[210:213], v[126:129]
	v_mfma_f32_16x16x32_bf16 v[122:125], v[186:189], v[210:213], v[122:125]
	v_mfma_f32_16x16x32_bf16 v[118:121], v[178:181], v[218:221], v[118:121]
	v_mfma_f32_16x16x32_bf16 v[114:117], v[186:189], v[218:221], v[114:117]
	v_mfma_f32_16x16x32_bf16 v[110:113], v[178:181], v[226:229], v[110:113]
	v_mfma_f32_16x16x32_bf16 v[106:109], v[186:189], v[226:229], v[106:109]
	v_mfma_f32_16x16x32_bf16 v[102:105], v[178:181], v[234:237], v[102:105]
	v_mfma_f32_16x16x32_bf16 v[98:101], v[186:189], v[234:237], v[98:101]
	s_setprio 0
	s_setprio 1
	v_mfma_f32_16x16x32_bf16 v[94:97], v[190:193], v[206:209], v[94:97]
	v_mfma_f32_16x16x32_bf16 v[90:93], v[198:201], v[206:209], v[90:93]
	v_mfma_f32_16x16x32_bf16 v[86:89], v[190:193], v[214:217], v[86:89]
	v_mfma_f32_16x16x32_bf16 v[82:85], v[198:201], v[214:217], v[82:85]
	v_mfma_f32_16x16x32_bf16 v[78:81], v[190:193], v[222:225], v[78:81]
	v_mfma_f32_16x16x32_bf16 v[74:77], v[198:201], v[222:225], v[74:77]
	v_mfma_f32_16x16x32_bf16 v[70:73], v[190:193], v[230:233], v[70:73]
	v_mfma_f32_16x16x32_bf16 v[66:69], v[198:201], v[230:233], v[66:69]
	v_mfma_f32_16x16x32_bf16 v[94:97], v[194:197], v[210:213], v[94:97]
	v_mfma_f32_16x16x32_bf16 v[90:93], v[202:205], v[210:213], v[90:93]
	v_mfma_f32_16x16x32_bf16 v[86:89], v[194:197], v[218:221], v[86:89]
	v_mfma_f32_16x16x32_bf16 v[82:85], v[202:205], v[218:221], v[82:85]
	v_mfma_f32_16x16x32_bf16 v[78:81], v[194:197], v[226:229], v[78:81]
	v_mfma_f32_16x16x32_bf16 v[74:77], v[202:205], v[226:229], v[74:77]
	v_mfma_f32_16x16x32_bf16 v[70:73], v[194:197], v[234:237], v[70:73]
	v_mfma_f32_16x16x32_bf16 v[66:69], v[202:205], v[234:237], v[66:69]
	s_setprio 0
	s_barrier
	s_add_i32 s86, s75, s9
	s_mov_b32 m0, s86
	ds_read_b128 v[206:209], v176 offset:16384
	ds_read_b128 v[210:213], v176 offset:17408
	ds_read_b128 v[214:217], v176 offset:18432
	ds_read_b128 v[218:221], v176 offset:19456
	ds_read_b128 v[222:225], v176 offset:20480
	ds_read_b128 v[226:229], v176 offset:21504
	ds_read_b128 v[230:233], v176 offset:22528
	ds_read_b128 v[234:237], v176 offset:23552
	global_load_lds_dwordx4 v140, s[60:61]
	s_add_i32 m0, s86, 0x2000
	s_add_u32 s86, s60, 0x40000
	s_addc_u32 s87, s61, 0
	s_add_i32 s88, s76, s9
	global_load_lds_dwordx4 v142, s[60:61]
	s_mov_b32 m0, s88
	s_nop 0
	global_load_lds_dwordx4 v140, s[86:87]
	s_add_i32 m0, s88, 0x2000
	s_nop 0
	global_load_lds_dwordx4 v142, s[86:87]
	s_mov_b32 m0, s66
	s_nop 0
	global_load_lds_dwordx4 v138, s[100:101]
	s_mov_b32 m0, s67
	s_nop 0
	global_load_lds_dwordx4 v244, s[100:101]
	s_waitcnt vmcnt(8)
	s_waitcnt lgkmcnt(0)
	s_barrier
	s_setprio 1
	s_waitcnt lgkmcnt(0)
	v_mfma_f32_16x16x32_bf16 v[62:65], v[132:135], v[206:209], v[62:65]
	v_mfma_f32_16x16x32_bf16 v[58:61], v[182:185], v[206:209], v[58:61]
	v_mfma_f32_16x16x32_bf16 v[54:57], v[132:135], v[214:217], v[54:57]
	v_mfma_f32_16x16x32_bf16 v[50:53], v[182:185], v[214:217], v[50:53]
	v_mfma_f32_16x16x32_bf16 v[46:49], v[132:135], v[222:225], v[46:49]
	v_mfma_f32_16x16x32_bf16 v[42:45], v[182:185], v[222:225], v[42:45]
	v_mfma_f32_16x16x32_bf16 v[38:41], v[132:135], v[230:233], v[38:41]
	v_mfma_f32_16x16x32_bf16 v[34:37], v[182:185], v[230:233], v[34:37]
	v_mfma_f32_16x16x32_bf16 v[62:65], v[178:181], v[210:213], v[62:65]
	v_mfma_f32_16x16x32_bf16 v[58:61], v[186:189], v[210:213], v[58:61]
	v_mfma_f32_16x16x32_bf16 v[54:57], v[178:181], v[218:221], v[54:57]
	v_mfma_f32_16x16x32_bf16 v[50:53], v[186:189], v[218:221], v[50:53]
	v_mfma_f32_16x16x32_bf16 v[46:49], v[178:181], v[226:229], v[46:49]
	v_mfma_f32_16x16x32_bf16 v[42:45], v[186:189], v[226:229], v[42:45]
	v_mfma_f32_16x16x32_bf16 v[38:41], v[178:181], v[234:237], v[38:41]
	v_mfma_f32_16x16x32_bf16 v[34:37], v[186:189], v[234:237], v[34:37]
	s_setprio 0
	s_setprio 1
	v_mfma_f32_16x16x32_bf16 v[30:33], v[190:193], v[206:209], v[30:33]
	v_mfma_f32_16x16x32_bf16 v[26:29], v[198:201], v[206:209], v[26:29]
	v_mfma_f32_16x16x32_bf16 v[22:25], v[190:193], v[214:217], v[22:25]
	v_mfma_f32_16x16x32_bf16 v[18:21], v[198:201], v[214:217], v[18:21]
	v_mfma_f32_16x16x32_bf16 v[14:17], v[190:193], v[222:225], v[14:17]
	v_mfma_f32_16x16x32_bf16 v[10:13], v[198:201], v[222:225], v[10:13]
	v_mfma_f32_16x16x32_bf16 v[6:9], v[190:193], v[230:233], v[6:9]
	v_mfma_f32_16x16x32_bf16 v[2:5], v[198:201], v[230:233], v[2:5]
	v_mfma_f32_16x16x32_bf16 v[30:33], v[194:197], v[210:213], v[30:33]
	v_mfma_f32_16x16x32_bf16 v[26:29], v[202:205], v[210:213], v[26:29]
	v_mfma_f32_16x16x32_bf16 v[22:25], v[194:197], v[218:221], v[22:25]
	v_mfma_f32_16x16x32_bf16 v[18:21], v[202:205], v[218:221], v[18:21]
	v_mfma_f32_16x16x32_bf16 v[14:17], v[194:197], v[226:229], v[14:17]
	v_mfma_f32_16x16x32_bf16 v[10:13], v[202:205], v[226:229], v[10:13]
	v_mfma_f32_16x16x32_bf16 v[6:9], v[194:197], v[234:237], v[6:9]
	v_mfma_f32_16x16x32_bf16 v[2:5], v[202:205], v[234:237], v[2:5]
	s_setprio 0
	s_barrier
; #define PG8_STAGE(bufoff, gbase, voff) do { _Pragma("unroll") for (int _i = 0; _i < 2; ++_i) \
;         __builtin_amdgcn_global_load_lds((const unsigned*)((const char*)(gbase) + (voff)[_i]), (PG8_LAS unsigned*)(lds + (bufoff) + ldsw + _i * 8192), 16, 0, 0); } while (0)
; #define PG8_LDA(dst, b, h) do { _Pragma("unroll") for (int m = 0; m < 4; ++m) _Pragma("unroll") for (int k = 0; k < 2; ++k) dst[m][k] = *(const PG8_LAS bf16x8*)(lds + PG8_SA(b, h) + aoff + m * 2048 + k * 1024); } while (0)
; #define PG8_LDB(dst, b, h) do { _Pragma("unroll") for (int n = 0; n < 2; ++n) _Pragma("unroll") for (int k = 0; k < 2; ++k) dst[n][k] = *(const PG8_LAS bf16x8*)(lds + PG8_SB(b, h) + boff + n * 2048 + k * 1024); } while (0)
; #define PG8_MMA(ai, bj, At, Bt) do { __builtin_amdgcn_s_setprio(1); _Pragma("unroll") for (int m = 0; m < 4; ++m) _Pragma("unroll") for (int n = 0; n < 2; ++n) _Pragma("unroll") for (int k = 0; k < 2; ++k) \
;         acc[ai][bj][m][n] = __builtin_amdgcn_mfma_f32_16x16x32_bf16(Bt[n][k], At[m][k], acc[ai][bj][m][n], 0, 0, 0); __builtin_amdgcn_s_setprio(0); } while (0)
; #define PG8_WAIT_V(n) asm volatile("s_waitcnt vmcnt(" #n ")" ::: "memory")
; #define PG8_WAIT_L(n) asm volatile("s_waitcnt lgkmcnt(" #n ")" ::: "memory")
; #define PG8_BAR __builtin_amdgcn_s_barrier()
; #define PG8_SCHED __builtin_amdgcn_sched_barrier(0)
; template <class Epi, bool ALIGN_EPI, bool ABLK = false>
; __device__ __forceinline__ void gemm_phase(PG8_LAS unsigned char* lds, const Gemm g, const StaticOrder& S, const Epi& E) {
;     ...
;             PG8_LDB(B0, 1, 0); PG8_LDB(B1, 1, 1); PG8_SCHED; PG8_LDA(At, 1, 0); PG8_STAGE(PG8_SA(0, 1), a2 + hstepA, voffA);
;             PG8_WAIT_V(8); PG8_WAIT_L(0); PG8_BAR; PG8_MMA(0, 0, At, B0); PG8_MMA(0, 1, At, B1); PG8_BAR; PG8_SCHED;
;             PG8_LDA(At, 1, 1); PG8_STAGE(PG8_SB(1, 0), b3, voffB); PG8_STAGE(PG8_SB(1, 1), b3 + hstepB, voffB); PG8_STAGE(PG8_SA(1, 0), a3, voffA);
;             PG8_WAIT_V(8); PG8_WAIT_L(0); PG8_BAR; PG8_MMA(1, 0, At, B0); PG8_MMA(1, 1, At, B1); PG8_BAR; PG8_SCHED;
;         }
	s_add_i32 s84, 0, 0x18000
	s_add_i32 s85, 0, 0x1c000
	ds_read_b128 v[132:135], v251 offset:32768
	ds_read_b128 v[178:181], v251 offset:33792
	ds_read_b128 v[182:185], v251 offset:34816
	ds_read_b128 v[186:189], v251 offset:35840
	ds_read_b128 v[190:193], v251 offset:49152
	ds_read_b128 v[194:197], v251 offset:50176
	ds_read_b128 v[198:201], v251 offset:51200
	ds_read_b128 v[202:205], v251 offset:52224
	s_mov_b32 m0, s68
	ds_read_b128 v[206:209], v176 offset:32768
	ds_read_b128 v[210:213], v176 offset:33792
	ds_read_b128 v[214:217], v176 offset:34816
	ds_read_b128 v[218:221], v176 offset:35840
	ds_read_b128 v[222:225], v176 offset:36864
	ds_read_b128 v[226:229], v176 offset:37888
	ds_read_b128 v[230:233], v176 offset:38912
	ds_read_b128 v[234:237], v176 offset:39936
	global_load_lds_dwordx4 v245, s[100:101]
	s_mov_b32 m0, s69
	s_nop 0
	global_load_lds_dwordx4 v246, s[100:101]
	s_waitcnt vmcnt(8)
	s_waitcnt lgkmcnt(0)
	s_barrier
	s_setprio 1
	s_waitcnt lgkmcnt(0)
	v_mfma_f32_16x16x32_bf16 v[126:129], v[132:135], v[206:209], v[126:129]
	v_mfma_f32_16x16x32_bf16 v[122:125], v[182:185], v[206:209], v[122:125]
	v_mfma_f32_16x16x32_bf16 v[118:121], v[132:135], v[214:217], v[118:121]
	v_mfma_f32_16x16x32_bf16 v[114:117], v[182:185], v[214:217], v[114:117]
	v_mfma_f32_16x16x32_bf16 v[110:113], v[132:135], v[222:225], v[110:113]
	v_mfma_f32_16x16x32_bf16 v[106:109], v[182:185], v[222:225], v[106:109]
	v_mfma_f32_16x16x32_bf16 v[102:105], v[132:135], v[230:233], v[102:105]
	v_mfma_f32_16x16x32_bf16 v[98:101], v[182:185], v[230:233], v[98:101]
	v_mfma_f32_16x16x32_bf16 v[126:129], v[178:181], v[210:213], v[126:129]
	v_mfma_f32_16x16x32_bf16 v[122:125], v[186:189], v[210:213], v[122:125]
	v_mfma_f32_16x16x32_bf16 v[118:121], v[178:181], v[218:221], v[118:121]
	v_mfma_f32_16x16x32_bf16 v[114:117], v[186:189], v[218:221], v[114:117]
	v_mfma_f32_16x16x32_bf16 v[110:113], v[178:181], v[226:229], v[110:113]
	v_mfma_f32_16x16x32_bf16 v[106:109], v[186:189], v[226:229], v[106:109]
	v_mfma_f32_16x16x32_bf16 v[102:105], v[178:181], v[234:237], v[102:105]
	v_mfma_f32_16x16x32_bf16 v[98:101], v[186:189], v[234:237], v[98:101]
	s_setprio 0
	s_setprio 1
	v_mfma_f32_16x16x32_bf16 v[94:97], v[190:193], v[206:209], v[94:97]
	v_mfma_f32_16x16x32_bf16 v[90:93], v[198:201], v[206:209], v[90:93]
	v_mfma_f32_16x16x32_bf16 v[86:89], v[190:193], v[214:217], v[86:89]
	v_mfma_f32_16x16x32_bf16 v[82:85], v[198:201], v[214:217], v[82:85]
	v_mfma_f32_16x16x32_bf16 v[78:81], v[190:193], v[222:225], v[78:81]
	v_mfma_f32_16x16x32_bf16 v[74:77], v[198:201], v[222:225], v[74:77]
	v_mfma_f32_16x16x32_bf16 v[70:73], v[190:193], v[230:233], v[70:73]
	v_mfma_f32_16x16x32_bf16 v[66:69], v[198:201], v[230:233], v[66:69]
	v_mfma_f32_16x16x32_bf16 v[94:97], v[194:197], v[210:213], v[94:97]
	v_mfma_f32_16x16x32_bf16 v[90:93], v[202:205], v[210:213], v[90:93]
	v_mfma_f32_16x16x32_bf16 v[86:89], v[194:197], v[218:221], v[86:89]
	v_mfma_f32_16x16x32_bf16 v[82:85], v[202:205], v[218:221], v[82:85]
	v_mfma_f32_16x16x32_bf16 v[78:81], v[194:197], v[226:229], v[78:81]
	v_mfma_f32_16x16x32_bf16 v[74:77], v[202:205], v[226:229], v[74:77]
	v_mfma_f32_16x16x32_bf16 v[70:73], v[194:197], v[234:237], v[70:73]
	v_mfma_f32_16x16x32_bf16 v[66:69], v[202:205], v[234:237], v[66:69]
	s_setprio 0
	s_barrier
	s_add_i32 s84, s84, s9
	s_add_u32 s60, s60, s28
	s_addc_u32 s61, s61, s29
	s_mov_b32 m0, s84
	ds_read_b128 v[206:209], v176 offset:49152
	ds_read_b128 v[210:213], v176 offset:50176
	ds_read_b128 v[214:217], v176 offset:51200
	ds_read_b128 v[218:221], v176 offset:52224
	ds_read_b128 v[222:225], v176 offset:53248
	ds_read_b128 v[226:229], v176 offset:54272
	ds_read_b128 v[230:233], v176 offset:55296
	ds_read_b128 v[234:237], v176 offset:56320
	global_load_lds_dwordx4 v140, s[60:61]
	s_add_i32 m0, s84, 0x2000
	s_add_i32 s84, s85, s9
	global_load_lds_dwordx4 v142, s[60:61]
	s_add_u32 s60, s60, 0x40000
	s_addc_u32 s61, s61, 0
	s_mov_b32 m0, s84
	s_nop 0
	global_load_lds_dwordx4 v140, s[60:61]
	s_add_i32 m0, s84, 0x2000
	s_nop 0
	global_load_lds_dwordx4 v142, s[60:61]
	s_mov_b32 m0, s70
	s_nop 0
	global_load_lds_dwordx4 v247, s[100:101]
	s_mov_b32 m0, s72
	s_nop 0
	global_load_lds_dwordx4 v248, s[100:101]
	s_waitcnt vmcnt(8)
	s_waitcnt lgkmcnt(0)
	s_barrier
	s_setprio 1
	s_waitcnt lgkmcnt(0)
	v_mfma_f32_16x16x32_bf16 v[62:65], v[132:135], v[206:209], v[62:65]
	v_mfma_f32_16x16x32_bf16 v[58:61], v[182:185], v[206:209], v[58:61]
	v_mfma_f32_16x16x32_bf16 v[54:57], v[132:135], v[214:217], v[54:57]
	v_mfma_f32_16x16x32_bf16 v[50:53], v[182:185], v[214:217], v[50:53]
	v_mfma_f32_16x16x32_bf16 v[46:49], v[132:135], v[222:225], v[46:49]
	v_mfma_f32_16x16x32_bf16 v[42:45], v[182:185], v[222:225], v[42:45]
	v_mfma_f32_16x16x32_bf16 v[38:41], v[132:135], v[230:233], v[38:41]
	v_mfma_f32_16x16x32_bf16 v[34:37], v[182:185], v[230:233], v[34:37]
	v_mfma_f32_16x16x32_bf16 v[62:65], v[178:181], v[210:213], v[62:65]
	v_mfma_f32_16x16x32_bf16 v[58:61], v[186:189], v[210:213], v[58:61]
	v_mfma_f32_16x16x32_bf16 v[54:57], v[178:181], v[218:221], v[54:57]
	v_mfma_f32_16x16x32_bf16 v[50:53], v[186:189], v[218:221], v[50:53]
	v_mfma_f32_16x16x32_bf16 v[46:49], v[178:181], v[226:229], v[46:49]
	v_mfma_f32_16x16x32_bf16 v[42:45], v[186:189], v[226:229], v[42:45]
	v_mfma_f32_16x16x32_bf16 v[38:41], v[178:181], v[234:237], v[38:41]
	v_mfma_f32_16x16x32_bf16 v[34:37], v[186:189], v[234:237], v[34:37]
	s_setprio 0
	s_setprio 1
	v_mfma_f32_16x16x32_bf16 v[30:33], v[190:193], v[206:209], v[30:33]
	v_mfma_f32_16x16x32_bf16 v[26:29], v[198:201], v[206:209], v[26:29]
	v_mfma_f32_16x16x32_bf16 v[22:25], v[190:193], v[214:217], v[22:25]
	v_mfma_f32_16x16x32_bf16 v[18:21], v[198:201], v[214:217], v[18:21]
	v_mfma_f32_16x16x32_bf16 v[14:17], v[190:193], v[222:225], v[14:17]
	v_mfma_f32_16x16x32_bf16 v[10:13], v[198:201], v[222:225], v[10:13]
	v_mfma_f32_16x16x32_bf16 v[6:9], v[190:193], v[230:233], v[6:9]
	v_mfma_f32_16x16x32_bf16 v[2:5], v[198:201], v[230:233], v[2:5]
	v_mfma_f32_16x16x32_bf16 v[30:33], v[194:197], v[210:213], v[30:33]
	v_mfma_f32_16x16x32_bf16 v[26:29], v[202:205], v[210:213], v[26:29]
	v_mfma_f32_16x16x32_bf16 v[22:25], v[194:197], v[218:221], v[22:25]
	v_mfma_f32_16x16x32_bf16 v[18:21], v[202:205], v[218:221], v[18:21]
	v_mfma_f32_16x16x32_bf16 v[14:17], v[194:197], v[226:229], v[14:17]
	v_mfma_f32_16x16x32_bf16 v[10:13], v[202:205], v[226:229], v[10:13]
	v_mfma_f32_16x16x32_bf16 v[6:9], v[194:197], v[234:237], v[6:9]
	v_mfma_f32_16x16x32_bf16 v[2:5], v[202:205], v[234:237], v[2:5]
	s_setprio 0
	s_barrier
	s_add_i32 s83, s83, 2
	s_add_u32 s81, s81, 0x100
	s_addc_u32 s82, s82, 0
	s_add_u32 s58, s58, 0x10000
	s_addc_u32 s59, s59, 0
	s_cmp_gt_u32 s83, 13
	s_cbranch_scc0 .LBB0_2495
	s_and_b64 vcc, exec, s[36:37]
	s_cbranch_vccz .LBB0_2498
	s_barrier
